# phase A adaLN item: bias element loaded once at item start instead of re-loaded (cold miss + vmcnt(0)) in each of the 3 epilogue iterations
# baseline (speedup 1.0000x reference)
.LBB0_88:
	s_or_b64 exec, exec, s[4:5]
	v_ashrrev_i32_e32 v8, 5, v70
	v_lshlrev_b32_e32 v2, 10, v8
	v_lshlrev_b32_e32 v0, 2, v70
	v_ashrrev_i32_e32 v3, 31, v2
	v_add_u32_e32 v48, 0xffffc000, v2
	v_and_b32_e32 v7, 0x7c, v0
	v_lshl_add_u64 v[0:1], v[2:3], 2, s[72:73]
	v_lshl_add_u64 v[4:5], v[48:49], 2, s[74:75]
	v_cmp_gt_i32_e32 vcc, 16, v8
	v_mov_b32_e32 v3, v49
	v_lshl_add_u64 v[12:13], v[2:3], 2, s[74:75]
	v_cndmask_b32_e32 v5, v5, v1, vcc
	v_cndmask_b32_e32 v4, v4, v0, vcc
	v_lshlrev_b32_e32 v0, 2, v7
	v_mov_b32_e32 v1, v49
	v_lshl_add_u64 v[74:75], v[4:5], 0, v[0:1]
	v_add_u32_e32 v4, 0x4000, v2
	v_ashrrev_i32_e32 v5, 31, v4
	v_lshl_add_u64 v[10:11], v[4:5], 2, s[72:73]
	v_cmp_gt_i32_e32 vcc, 0, v8
	global_load_dwordx4 v[32:35], v[74:75], off
	s_movk_i32 s4, 0xffef
	v_cndmask_b32_e32 v11, v13, v11, vcc
	v_cndmask_b32_e32 v10, v12, v10, vcc
	v_lshl_add_u64 v[76:77], v[10:11], 0, v[0:1]
	global_load_dwordx4 v[36:39], v[76:77], off
	v_add_u32_e32 v2, 0x8000, v2
	v_cmp_gt_i32_e32 vcc, -16, v8
	v_cmp_lt_i32_e64 s[4:5], s4, v8
	v_mov_b32_e32 v48, v4
	v_ashrrev_i32_e32 v3, 31, v2
	s_and_saveexec_b64 s[38:39], s[4:5]
	s_xor_b64 s[4:5], exec, s[38:39]
	v_lshl_add_u64 v[4:5], v[48:49], 2, s[74:75]
	s_andn2_saveexec_b64 s[4:5], s[4:5]
	v_lshl_add_u64 v[4:5], v[2:3], 2, s[72:73]
	s_or_b64 exec, exec, s[4:5]
	v_mov_b32_e32 v1, v49
	v_lshlrev_b32_e32 v78, 5, v6
	v_lshl_add_u64 v[4:5], v[4:5], 0, v[0:1]
	v_and_b32_e32 v45, 31, v70
	v_or_b32_e32 v202, v45, v78
	v_ashrrev_i32_e32 v203, 31, v202
	v_lshl_add_u64 v[202:203], v[202:203], 2, s[78:79]
	global_load_dword v200, v[202:203], off
	v_bfe_u32 v64, v70, 5, 1
	global_load_dwordx4 v[40:43], v[4:5], off
	v_ashrrev_i32_e32 v4, 2, v70
	v_ashrrev_i32_e32 v79, 31, v78
	v_and_or_b32 v68, v4, -16, v64
	v_lshl_add_u64 v[4:5], v[78:79], 2, s[76:77]
	v_lshlrev_b32_e32 v72, 2, v45
	v_mov_b32_e32 v73, v49
	v_lshl_add_u64 v[80:81], v[4:5], 0, v[72:73]
	v_or_b32_e32 v6, 2, v68
	v_mad_i64_i32 v[10:11], s[4:5], v6, s58, v[80:81]
	v_or_b32_e32 v6, 4, v68
	v_mad_i64_i32 v[12:13], s[4:5], v6, s58, v[80:81]
	v_or_b32_e32 v6, 6, v68
	v_mad_i64_i32 v[14:15], s[4:5], v6, s58, v[80:81]
	v_or_b32_e32 v6, 8, v68
	v_mad_i64_i32 v[16:17], s[4:5], v6, s58, v[80:81]
	v_or_b32_e32 v6, 10, v68
	v_mad_i64_i32 v[18:19], s[4:5], v6, s58, v[80:81]
	v_or_b32_e32 v6, 12, v68
	v_mad_i64_i32 v[20:21], s[4:5], v6, s58, v[80:81]
	v_or_b32_e32 v6, 14, v68
	v_mad_i64_i32 v[4:5], s[4:5], v68, s58, v[80:81]
	v_mad_i64_i32 v[22:23], s[4:5], v6, s58, v[80:81]
	v_add_u32_e32 v6, 0x82, v68
	global_load_dword v123, v[4:5], off
	global_load_dword v122, v[10:11], off
	global_load_dword v121, v[12:13], off
	global_load_dword v120, v[14:15], off
	global_load_dword v117, v[16:17], off
	global_load_dword v106, v[18:19], off
	global_load_dword v71, v[20:21], off
	global_load_dword v112, v[22:23], off
	v_mad_i64_i32 v[10:11], s[4:5], v6, s58, v[80:81]
	v_add_u32_e32 v6, 0x84, v68
	v_mad_i64_i32 v[12:13], s[4:5], v6, s58, v[80:81]
	v_add_u32_e32 v6, 0x86, v68
	v_mad_i64_i32 v[14:15], s[4:5], v6, s58, v[80:81]
	v_add_u32_e32 v6, 0x88, v68
	v_mad_i64_i32 v[16:17], s[4:5], v6, s58, v[80:81]
	v_add_u32_e32 v6, 0x8a, v68
	v_mad_i64_i32 v[18:19], s[4:5], v6, s58, v[80:81]
	v_add_u32_e32 v6, 0x8c, v68
	v_add_u32_e32 v4, 0x80, v68
	v_mad_i64_i32 v[20:21], s[4:5], v6, s58, v[80:81]
	v_add_u32_e32 v6, 0x8e, v68
	v_mad_i64_i32 v[4:5], s[4:5], v4, s58, v[80:81]
	v_mad_i64_i32 v[22:23], s[4:5], v6, s58, v[80:81]
	v_add_u32_e32 v6, 0x102, v68
	global_load_dword v127, v[4:5], off
	global_load_dword v126, v[10:11], off
	global_load_dword v125, v[12:13], off
	global_load_dword v124, v[14:15], off
	global_load_dword v119, v[16:17], off
	global_load_dword v110, v[18:19], off
	global_load_dword v73, v[20:21], off
	global_load_dword v114, v[22:23], off
	v_mad_i64_i32 v[10:11], s[4:5], v6, s58, v[80:81]
	v_add_u32_e32 v6, 0x104, v68
	v_mad_i64_i32 v[12:13], s[4:5], v6, s58, v[80:81]
	v_add_u32_e32 v6, 0x106, v68
	v_mad_i64_i32 v[14:15], s[4:5], v6, s58, v[80:81]
	v_add_u32_e32 v6, 0x108, v68
	v_mad_i64_i32 v[16:17], s[4:5], v6, s58, v[80:81]
	v_add_u32_e32 v6, 0x10a, v68
	v_add_u32_e32 v4, 0x100, v68
	v_mad_i64_i32 v[18:19], s[4:5], v6, s58, v[80:81]
	v_add_u32_e32 v6, 0x10c, v68
	v_mad_i64_i32 v[4:5], s[4:5], v4, s58, v[80:81]
	v_mad_i64_i32 v[20:21], s[4:5], v6, s58, v[80:81]
	v_add_u32_e32 v6, 0x10e, v68
	v_mad_i64_i32 v[22:23], s[4:5], v6, s58, v[80:81]
	global_load_dword v128, v[4:5], off
	global_load_dword v118, v[10:11], off
	global_load_dword v115, v[12:13], off
	global_load_dword v113, v[14:15], off
	global_load_dword v111, v[16:17], off
	global_load_dword v108, v[18:19], off
	global_load_dword v107, v[20:21], off
	global_load_dword v116, v[22:23], off
	v_ashrrev_i32_e32 v79, 6, v70
	v_lshl_or_b32 v4, v79, 4, v64
	v_lshlrev_b32_e32 v6, 2, v8
	v_mul_lo_u32 v8, v4, s56
	v_lshl_add_u64 v[2:3], v[2:3], 2, s[72:73]
	v_lshl_add_u64 v[4:5], v[48:49], 2, s[74:75]
	v_cndmask_b32_e32 v3, v5, v3, vcc
	v_cndmask_b32_e32 v2, v4, v2, vcc
	v_mul_u32_u24_e32 v7, 0x104, v7
	v_lshl_add_u64 v[82:83], v[2:3], 0, v[0:1]
	v_mov_b32_e32 v0, 0
	s_mov_b32 s84, 0
	s_mov_b64 s[38:39], -1
	v_add_u32_e32 v48, v6, v7
	v_add_u32_e32 v109, v72, v8
	v_mov_b32_e32 v1, v0
	v_mov_b32_e32 v2, v0
	v_mov_b32_e32 v3, v0
	v_mov_b32_e32 v4, v0
	v_mov_b32_e32 v5, v0
	v_mov_b32_e32 v6, v0
	v_mov_b32_e32 v7, v0
	v_mov_b32_e32 v8, v0
	v_mov_b32_e32 v9, v0
	v_mov_b32_e32 v10, v0
	v_mov_b32_e32 v11, v0
	v_mov_b32_e32 v12, v0
	v_mov_b32_e32 v13, v0
	v_mov_b32_e32 v14, v0
	v_mov_b32_e32 v15, v0
	v_mov_b32_e32 v16, v0
	v_mov_b32_e32 v17, v0
	v_mov_b32_e32 v18, v0
	v_mov_b32_e32 v19, v0
	v_mov_b32_e32 v20, v0
	v_mov_b32_e32 v21, v0
	v_mov_b32_e32 v22, v0
	v_mov_b32_e32 v23, v0
	v_mov_b32_e32 v24, v0
	v_mov_b32_e32 v25, v0
	v_mov_b32_e32 v26, v0
	v_mov_b32_e32 v27, v0
	v_mov_b32_e32 v28, v0
	v_mov_b32_e32 v29, v0
	v_mov_b32_e32 v30, v0
	v_mov_b32_e32 v31, v0
.LBB0_93:
	s_waitcnt vmcnt(10)
	v_mul_f32_e32 v84, 0xbfb8aa3b, v32
	v_mul_f32_e32 v85, 0xbfb8aa3b, v33
	v_mul_f32_e32 v86, 0xbfb8aa3b, v34
	v_mul_f32_e32 v87, 0xbfb8aa3b, v35
	s_waitcnt vmcnt(9)
	v_mul_f32_e32 v88, 0xbfb8aa3b, v36
	v_mul_f32_e32 v89, 0xbfb8aa3b, v37
	v_mul_f32_e32 v90, 0xbfb8aa3b, v38
	v_mul_f32_e32 v91, 0xbfb8aa3b, v39
	s_waitcnt vmcnt(8)
	v_mul_f32_e32 v92, 0xbfb8aa3b, v40
	v_mul_f32_e32 v93, 0xbfb8aa3b, v41
	v_mul_f32_e32 v94, 0xbfb8aa3b, v42
	v_mul_f32_e32 v95, 0xbfb8aa3b, v43
	v_exp_f32_e32 v129, v84
	v_exp_f32_e32 v132, v85
	v_exp_f32_e32 v133, v86
	v_exp_f32_e32 v134, v87
	v_exp_f32_e32 v135, v88
	v_exp_f32_e32 v142, v89
	v_exp_f32_e32 v143, v90
	v_exp_f32_e32 v144, v91
	v_exp_f32_e32 v145, v92
	v_exp_f32_e32 v146, v93
	v_exp_f32_e32 v147, v94
	v_exp_f32_e32 v148, v95
	v_add_f32_e32 v129, 1.0, v129
	v_add_f32_e32 v132, 1.0, v132
	v_add_f32_e32 v133, 1.0, v133
	v_add_f32_e32 v134, 1.0, v134
	v_add_f32_e32 v135, 1.0, v135
	v_add_f32_e32 v142, 1.0, v142
	v_add_f32_e32 v143, 1.0, v143
	v_add_f32_e32 v144, 1.0, v144
	v_add_f32_e32 v145, 1.0, v145
	v_add_f32_e32 v146, 1.0, v146
	v_add_f32_e32 v147, 1.0, v147
	v_add_f32_e32 v148, 1.0, v148
	v_rcp_f32_e32 v129, v129
	v_rcp_f32_e32 v132, v132
	v_rcp_f32_e32 v133, v133
	v_rcp_f32_e32 v134, v134
	v_rcp_f32_e32 v135, v135
	v_rcp_f32_e32 v142, v142
	v_rcp_f32_e32 v143, v143
	v_rcp_f32_e32 v144, v144
	v_rcp_f32_e32 v145, v145
	v_rcp_f32_e32 v146, v146
	v_rcp_f32_e32 v147, v147
	v_rcp_f32_e32 v148, v148
	s_or_b32 s41, s84, 0x180
	v_add_u32_e32 v92, s41, v68
	s_lshl_b64 s[4:5], s[84:85], 2
	v_or_b32_e32 v130, 8, v92
	v_or_b32_e32 v136, 10, v92
	v_lshl_add_u64 v[84:85], v[74:75], 0, s[4:5]
	v_lshl_add_u64 v[86:87], v[76:77], 0, s[4:5]
	v_lshl_add_u64 v[88:89], v[82:83], 0, s[4:5]
	v_or_b32_e32 v93, 2, v92
	v_or_b32_e32 v94, 4, v92
	v_or_b32_e32 v96, 6, v92
	v_or_b32_e32 v138, 12, v92
	v_or_b32_e32 v140, 14, v92
	v_mad_i64_i32 v[130:131], s[4:5], v130, s58, v[80:81]
	v_mad_i64_i32 v[136:137], s[4:5], v136, s58, v[80:81]
	v_mul_f32_e32 v32, v32, v129
	v_mul_f32_e32 v33, v33, v132
	v_mul_f32_e32 v34, v34, v133
	v_mul_f32_e32 v35, v35, v134
	v_mul_f32_e32 v36, v36, v135
	v_mul_f32_e32 v37, v37, v142
	v_mul_f32_e32 v38, v38, v143
	v_mul_f32_e32 v39, v39, v144
	v_mul_f32_e32 v40, v40, v145
	v_mul_f32_e32 v41, v41, v146
	v_mul_f32_e32 v42, v42, v147
	v_mul_f32_e32 v43, v43, v148
	s_waitcnt lgkmcnt(0)
	s_barrier
	v_mad_i64_i32 v[90:91], s[4:5], v92, s58, v[80:81]
	v_mad_i64_i32 v[92:93], s[4:5], v93, s58, v[80:81]
	v_mad_i64_i32 v[94:95], s[4:5], v94, s58, v[80:81]
	v_mad_i64_i32 v[96:97], s[4:5], v96, s58, v[80:81]
	v_mad_i64_i32 v[138:139], s[4:5], v138, s58, v[80:81]
	v_mad_i64_i32 v[140:141], s[4:5], v140, s58, v[80:81]
	ds_write2_b32 v48, v32, v36 offset1:16
	ds_write2_b32 v48, v34, v38 offset0:130 offset1:146
	ds_write2_b32 v48, v40, v33 offset0:32 offset1:65
	ds_write2_b32 v48, v37, v41 offset0:81 offset1:97
	ds_write2_b32 v48, v42, v35 offset0:162 offset1:195
	ds_write2_b32 v48, v39, v43 offset0:211 offset1:227
	s_waitcnt lgkmcnt(0)
	s_barrier
	global_load_dwordx4 v[40:43], v[84:85], off offset:512
	global_load_dwordx4 v[36:39], v[86:87], off offset:512
	global_load_dwordx4 v[32:35], v[88:89], off offset:512
	global_load_dword v135, v[90:91], off
	global_load_dword v134, v[92:93], off
	global_load_dword v133, v[94:95], off
	global_load_dword v132, v[96:97], off
	s_nop 0
	global_load_dword v131, v[130:131], off
	s_nop 0
	global_load_dword v130, v[136:137], off
	global_load_dword v129, v[138:139], off
	s_nop 0
	global_load_dword v136, v[140:141], off
	s_or_b32 s40, s84, 0x80
	s_or_b32 s43, s84, 0x100
	s_and_b64 s[4:5], s[38:39], exec
	s_cselect_b32 s5, 0, 0
	s_cselect_b32 s4, 0x200, s41
	s_cselect_b32 s42, 0x200, s40
	s_cselect_b32 s40, 0x280, s43
	s_lshl_b64 s[4:5], s[4:5], 2
	v_cndmask_b32_e64 v90, 0, 1, s[38:39]
	s_and_b64 s[38:39], s[38:39], exec
	s_movk_i32 s84, 0x200
	s_cselect_b32 s38, 0x300, s41
	v_cmp_ne_u32_e32 vcc, 1, v90
	v_add_u32_e32 v139, 0x400, v109
	v_add_u32_e32 v138, 0x800, v109
	v_add_u32_e32 v137, 0xc00, v109
	ds_read2_b32 v[140:141], v109 offset1:32
	ds_read2_b32 v[142:143], v109 offset0:130 offset1:162
	ds_read2_b32 v[144:145], v139 offset0:4 offset1:36
	ds_read2_b32 v[146:147], v139 offset0:134 offset1:166
	ds_read2_b32 v[96:97], v138 offset0:8 offset1:40
	ds_read2_b32 v[94:95], v138 offset0:138 offset1:170
	ds_read2_b32 v[92:93], v137 offset0:12 offset1:44
	ds_read2_b32 v[90:91], v137 offset0:142 offset1:174
	s_waitcnt vmcnt(34) lgkmcnt(7)
	v_mfma_f32_32x32x2_f32 v[0:15], v140, v123, v[0:15]
	s_waitcnt vmcnt(9)
	v_mul_f32_e32 v140, 0xbfb8aa3b, v37
	v_exp_f32_e32 v153, v140
	s_waitcnt lgkmcnt(0)
	s_barrier
	v_mfma_f32_32x32x2_f32 v[16:31], v141, v123, v[16:31]
	v_mul_f32_e32 v123, 0xbfb8aa3b, v36
	v_mul_f32_e32 v141, 0xbfb8aa3b, v38
	v_exp_f32_e32 v123, v123
	v_exp_f32_e32 v154, v141
	v_add_f32_e32 v123, 1.0, v123
	v_rcp_f32_e32 v123, v123
	s_nop 0
	v_mul_f32_e32 v36, v36, v123
	v_mfma_f32_32x32x2_f32 v[0:15], v142, v122, v[0:15]
	v_mul_f32_e32 v142, 0xbfb8aa3b, v39
	v_exp_f32_e32 v155, v142
	v_mfma_f32_32x32x2_f32 v[16:31], v143, v122, v[16:31]
	v_mul_f32_e32 v122, 0xbfb8aa3b, v43
	s_waitcnt vmcnt(8)
	v_mul_f32_e32 v143, 0xbfb8aa3b, v32
	v_exp_f32_e32 v122, v122
	v_exp_f32_e32 v156, v143
	v_add_f32_e32 v122, 1.0, v122
	v_rcp_f32_e32 v122, v122
	s_nop 0
	v_mul_f32_e32 v43, v43, v122
	v_mfma_f32_32x32x2_f32 v[0:15], v144, v121, v[0:15]
	v_mul_f32_e32 v144, 0xbfb8aa3b, v33
	v_exp_f32_e32 v157, v144
	v_mfma_f32_32x32x2_f32 v[16:31], v145, v121, v[16:31]
	v_mul_f32_e32 v121, 0xbfb8aa3b, v42
	v_mul_f32_e32 v145, 0xbfb8aa3b, v34
	v_exp_f32_e32 v152, v121
	v_exp_f32_e32 v158, v145
	v_mfma_f32_32x32x2_f32 v[0:15], v146, v120, v[0:15]
	v_mul_f32_e32 v146, 0xbfb8aa3b, v35
	v_exp_f32_e32 v159, v146
	v_mfma_f32_32x32x2_f32 v[16:31], v147, v120, v[16:31]
	v_mul_f32_e32 v120, 0xbfb8aa3b, v41
	v_exp_f32_e32 v151, v120
	v_mfma_f32_32x32x2_f32 v[0:15], v96, v117, v[0:15]
	v_mul_f32_e32 v96, 0xbfb8aa3b, v40
	v_exp_f32_e32 v150, v96
	v_mfma_f32_32x32x2_f32 v[16:31], v97, v117, v[16:31]
	v_add_u32_e32 v117, s42, v68
	v_mad_i64_i32 v[96:97], s[42:43], v117, s58, v[80:81]
	v_or_b32_e32 v140, 4, v117
	v_or_b32_e32 v142, 6, v117
	v_or_b32_e32 v144, 8, v117
	v_or_b32_e32 v146, 10, v117
	v_or_b32_e32 v147, 12, v117
	v_mad_i64_i32 v[140:141], s[42:43], v140, s58, v[80:81]
	v_mad_i64_i32 v[142:143], s[42:43], v142, s58, v[80:81]
	v_mad_i64_i32 v[144:145], s[42:43], v144, s58, v[80:81]
	v_mfma_f32_32x32x2_f32 v[0:15], v94, v106, v[0:15]
	v_or_b32_e32 v94, 2, v117
	v_or_b32_e32 v117, 14, v117
	v_mad_i64_i32 v[148:149], s[42:43], v117, s58, v[80:81]
	v_add_f32_e32 v117, 1.0, v151
	v_add_f32_e32 v151, 1.0, v153
	v_add_f32_e32 v153, 1.0, v155
	v_add_f32_e32 v155, 1.0, v157
	v_rcp_f32_e32 v117, v117
	v_rcp_f32_e32 v151, v151
	v_rcp_f32_e32 v153, v153
	v_rcp_f32_e32 v155, v155
	v_mad_i64_i32 v[120:121], s[42:43], v94, s58, v[80:81]
	v_mul_f32_e32 v41, v41, v117
	v_mfma_f32_32x32x2_f32 v[16:31], v95, v106, v[16:31]
	v_add_f32_e32 v106, 1.0, v150
	v_add_f32_e32 v150, 1.0, v152
	v_add_f32_e32 v152, 1.0, v154
	v_add_f32_e32 v154, 1.0, v156
	v_add_f32_e32 v156, 1.0, v159
	v_rcp_f32_e32 v106, v106
	v_rcp_f32_e32 v150, v150
	v_rcp_f32_e32 v152, v152
	v_rcp_f32_e32 v154, v154
	v_rcp_f32_e32 v156, v156
	v_mul_f32_e32 v40, v40, v106
	v_mul_f32_e32 v42, v42, v150
	v_mul_f32_e32 v37, v37, v151
	v_mul_f32_e32 v38, v38, v152
	v_mul_f32_e32 v39, v39, v153
	v_mfma_f32_32x32x2_f32 v[0:15], v92, v71, v[0:15]
	v_add_f32_e32 v92, 1.0, v158
	v_rcp_f32_e32 v92, v92
	v_mul_f32_e32 v32, v32, v154
	v_mul_f32_e32 v33, v33, v155
	v_mul_f32_e32 v35, v35, v156
	v_mul_f32_e32 v34, v34, v92
	v_mad_i64_i32 v[94:95], s[42:43], v146, s58, v[80:81]
	v_mad_i64_i32 v[146:147], s[42:43], v147, s58, v[80:81]
	ds_write2_b32 v48, v40, v36 offset1:16
	ds_write2_b32 v48, v42, v38 offset0:130 offset1:146
	ds_write2_b32 v48, v32, v41 offset0:32 offset1:65
	ds_write2_b32 v48, v37, v33 offset0:81 offset1:97
	ds_write2_b32 v48, v34, v43 offset0:162 offset1:195
	ds_write2_b32 v48, v39, v35 offset0:211 offset1:227
	s_waitcnt lgkmcnt(0)
	s_barrier
	v_mfma_f32_32x32x2_f32 v[16:31], v93, v71, v[16:31]
	global_load_dwordx4 v[40:43], v[84:85], off offset:1024
	global_load_dwordx4 v[36:39], v[86:87], off offset:1024
	global_load_dwordx4 v[32:35], v[88:89], off offset:1024
	global_load_dword v123, v[96:97], off
	global_load_dword v122, v[120:121], off
	s_nop 0
	global_load_dword v121, v[140:141], off
	global_load_dword v120, v[142:143], off
	global_load_dword v117, v[144:145], off
	global_load_dword v106, v[94:95], off
	global_load_dword v71, v[146:147], off
	v_mfma_f32_32x32x2_f32 v[0:15], v90, v112, v[0:15]
	v_mfma_f32_32x32x2_f32 v[16:31], v91, v112, v[16:31]
	global_load_dword v112, v[148:149], off
	ds_read2_b32 v[140:141], v109 offset1:32
	ds_read2_b32 v[142:143], v109 offset0:130 offset1:162
	ds_read2_b32 v[144:145], v139 offset0:4 offset1:36
	ds_read2_b32 v[146:147], v139 offset0:134 offset1:166
	ds_read2_b32 v[96:97], v138 offset0:8 offset1:40
	ds_read2_b32 v[94:95], v138 offset0:138 offset1:170
	ds_read2_b32 v[92:93], v137 offset0:12 offset1:44
	ds_read2_b32 v[90:91], v137 offset0:142 offset1:174
	s_waitcnt lgkmcnt(7)
	v_mfma_f32_32x32x2_f32 v[0:15], v140, v127, v[0:15]
	s_waitcnt vmcnt(9)
	v_mul_f32_e32 v140, 0xbfb8aa3b, v37
	v_exp_f32_e32 v153, v140
	s_waitcnt lgkmcnt(0)
	s_barrier
	v_mfma_f32_32x32x2_f32 v[16:31], v141, v127, v[16:31]
	v_mul_f32_e32 v127, 0xbfb8aa3b, v36
	v_mul_f32_e32 v141, 0xbfb8aa3b, v38
	v_exp_f32_e32 v127, v127
	v_exp_f32_e32 v154, v141
	v_add_f32_e32 v127, 1.0, v127
	v_rcp_f32_e32 v127, v127
	s_nop 0
	v_mul_f32_e32 v36, v36, v127
	v_mfma_f32_32x32x2_f32 v[0:15], v142, v126, v[0:15]
	v_mul_f32_e32 v142, 0xbfb8aa3b, v39
	v_exp_f32_e32 v155, v142
	v_mfma_f32_32x32x2_f32 v[16:31], v143, v126, v[16:31]
	v_mul_f32_e32 v126, 0xbfb8aa3b, v43
	s_waitcnt vmcnt(8)
	v_mul_f32_e32 v143, 0xbfb8aa3b, v32
	v_exp_f32_e32 v126, v126
	v_exp_f32_e32 v156, v143
	v_add_f32_e32 v126, 1.0, v126
	v_rcp_f32_e32 v126, v126
	s_nop 0
	v_mul_f32_e32 v43, v43, v126
	v_mfma_f32_32x32x2_f32 v[0:15], v144, v125, v[0:15]
	v_mul_f32_e32 v144, 0xbfb8aa3b, v33
	v_exp_f32_e32 v157, v144
	v_mfma_f32_32x32x2_f32 v[16:31], v145, v125, v[16:31]
	v_mul_f32_e32 v125, 0xbfb8aa3b, v42
	v_mul_f32_e32 v145, 0xbfb8aa3b, v34
	v_exp_f32_e32 v152, v125
	v_exp_f32_e32 v158, v145
	v_mfma_f32_32x32x2_f32 v[0:15], v146, v124, v[0:15]
	v_mul_f32_e32 v146, 0xbfb8aa3b, v35
	v_exp_f32_e32 v159, v146
	v_mfma_f32_32x32x2_f32 v[16:31], v147, v124, v[16:31]
	v_mul_f32_e32 v124, 0xbfb8aa3b, v41
	v_exp_f32_e32 v151, v124
	v_mfma_f32_32x32x2_f32 v[0:15], v96, v119, v[0:15]
	v_mul_f32_e32 v96, 0xbfb8aa3b, v40
	v_exp_f32_e32 v150, v96
	v_mfma_f32_32x32x2_f32 v[16:31], v97, v119, v[16:31]
	v_add_u32_e32 v119, s40, v68
	v_mad_i64_i32 v[96:97], s[40:41], v119, s58, v[80:81]
	v_or_b32_e32 v140, 4, v119
	v_or_b32_e32 v142, 6, v119
	v_or_b32_e32 v144, 8, v119
	v_or_b32_e32 v146, 10, v119
	v_or_b32_e32 v147, 12, v119
	v_mad_i64_i32 v[140:141], s[40:41], v140, s58, v[80:81]
	v_mad_i64_i32 v[142:143], s[40:41], v142, s58, v[80:81]
	v_mad_i64_i32 v[144:145], s[40:41], v144, s58, v[80:81]
	v_mfma_f32_32x32x2_f32 v[0:15], v94, v110, v[0:15]
	v_or_b32_e32 v94, 2, v119
	v_or_b32_e32 v119, 14, v119
	v_mad_i64_i32 v[148:149], s[40:41], v119, s58, v[80:81]
	v_add_f32_e32 v119, 1.0, v151
	v_add_f32_e32 v151, 1.0, v153
	v_add_f32_e32 v153, 1.0, v155
	v_add_f32_e32 v155, 1.0, v157
	v_rcp_f32_e32 v119, v119
	v_rcp_f32_e32 v151, v151
	v_rcp_f32_e32 v153, v153
	v_rcp_f32_e32 v155, v155
	v_mad_i64_i32 v[124:125], s[40:41], v94, s58, v[80:81]
	v_mul_f32_e32 v41, v41, v119
	v_mfma_f32_32x32x2_f32 v[16:31], v95, v110, v[16:31]
	v_add_f32_e32 v110, 1.0, v150
	v_add_f32_e32 v150, 1.0, v152
	v_add_f32_e32 v152, 1.0, v154
	v_add_f32_e32 v154, 1.0, v156
	v_add_f32_e32 v156, 1.0, v159
	v_rcp_f32_e32 v110, v110
	v_rcp_f32_e32 v150, v150
	v_rcp_f32_e32 v152, v152
	v_rcp_f32_e32 v154, v154
	v_rcp_f32_e32 v156, v156
	v_mul_f32_e32 v40, v40, v110
	v_mul_f32_e32 v42, v42, v150
	v_mul_f32_e32 v37, v37, v151
	v_mul_f32_e32 v38, v38, v152
	v_mul_f32_e32 v39, v39, v153
	v_mfma_f32_32x32x2_f32 v[0:15], v92, v73, v[0:15]
	v_add_f32_e32 v92, 1.0, v158
	v_rcp_f32_e32 v92, v92
	v_mul_f32_e32 v32, v32, v154
	v_mul_f32_e32 v33, v33, v155
	v_mul_f32_e32 v35, v35, v156
	v_mul_f32_e32 v34, v34, v92
	v_mad_i64_i32 v[94:95], s[40:41], v146, s58, v[80:81]
	v_mad_i64_i32 v[146:147], s[40:41], v147, s58, v[80:81]
	ds_write2_b32 v48, v40, v36 offset1:16
	ds_write2_b32 v48, v42, v38 offset0:130 offset1:146
	ds_write2_b32 v48, v32, v41 offset0:32 offset1:65
	ds_write2_b32 v48, v37, v33 offset0:81 offset1:97
	ds_write2_b32 v48, v34, v43 offset0:162 offset1:195
	ds_write2_b32 v48, v39, v35 offset0:211 offset1:227
	s_waitcnt lgkmcnt(0)
	s_barrier
	v_mfma_f32_32x32x2_f32 v[16:31], v93, v73, v[16:31]
	global_load_dwordx4 v[40:43], v[84:85], off offset:1536
	global_load_dwordx4 v[36:39], v[86:87], off offset:1536
	global_load_dwordx4 v[32:35], v[88:89], off offset:1536
	global_load_dword v127, v[96:97], off
	global_load_dword v126, v[124:125], off
	s_nop 0
	global_load_dword v125, v[140:141], off
	global_load_dword v124, v[142:143], off
	global_load_dword v119, v[144:145], off
	global_load_dword v110, v[94:95], off
	global_load_dword v73, v[146:147], off
	v_mfma_f32_32x32x2_f32 v[0:15], v90, v114, v[0:15]
	v_mfma_f32_32x32x2_f32 v[16:31], v91, v114, v[16:31]
	global_load_dword v114, v[148:149], off
	ds_read2_b32 v[140:141], v109 offset1:32
	ds_read2_b32 v[96:97], v109 offset0:130 offset1:162
	ds_read2_b32 v[94:95], v139 offset0:4 offset1:36
	ds_read2_b32 v[92:93], v139 offset0:134 offset1:166
	ds_read2_b32 v[90:91], v138 offset0:8 offset1:40
	ds_read2_b32 v[88:89], v138 offset0:138 offset1:170
	ds_read2_b32 v[86:87], v137 offset0:12 offset1:44
	ds_read2_b32 v[84:85], v137 offset0:142 offset1:174
	s_waitcnt lgkmcnt(7)
	v_mfma_f32_32x32x2_f32 v[16:31], v141, v128, v[16:31]
	s_waitcnt lgkmcnt(6)
	v_mfma_f32_32x32x2_f32 v[16:31], v97, v118, v[16:31]
	s_waitcnt lgkmcnt(5)
	v_mfma_f32_32x32x2_f32 v[16:31], v95, v115, v[16:31]
	s_waitcnt lgkmcnt(4)
	v_mfma_f32_32x32x2_f32 v[16:31], v93, v113, v[16:31]
	s_waitcnt lgkmcnt(3)
	v_mfma_f32_32x32x2_f32 v[16:31], v91, v111, v[16:31]
	s_waitcnt lgkmcnt(2)
	v_mfma_f32_32x32x2_f32 v[16:31], v89, v108, v[16:31]
	s_waitcnt lgkmcnt(1)
	v_mfma_f32_32x32x2_f32 v[16:31], v87, v107, v[16:31]
	s_waitcnt lgkmcnt(0)
	v_mfma_f32_32x32x2_f32 v[16:31], v85, v116, v[16:31]
	v_mfma_f32_32x32x2_f32 v[0:15], v140, v128, v[0:15]
	s_waitcnt vmcnt(10)
	v_mul_f32_e32 v85, 0xbfb8aa3b, v40
	v_mul_f32_e32 v87, 0xbfb8aa3b, v41
	v_mul_f32_e32 v89, 0xbfb8aa3b, v42
	v_mul_f32_e32 v91, 0xbfb8aa3b, v43
	s_waitcnt vmcnt(9)
	v_mul_f32_e32 v93, 0xbfb8aa3b, v36
	v_mul_f32_e32 v95, 0xbfb8aa3b, v37
	v_mul_f32_e32 v97, 0xbfb8aa3b, v38
	v_mul_f32_e32 v128, 0xbfb8aa3b, v39
	s_waitcnt vmcnt(8)
	v_mul_f32_e32 v146, 0xbfb8aa3b, v32
	v_mul_f32_e32 v147, 0xbfb8aa3b, v33
	v_mul_f32_e32 v148, 0xbfb8aa3b, v34
	v_mul_f32_e32 v149, 0xbfb8aa3b, v35
	v_exp_f32_e32 v85, v85
	v_exp_f32_e32 v87, v87
	v_exp_f32_e32 v89, v89
	v_mfma_f32_32x32x2_f32 v[0:15], v96, v118, v[0:15]
	v_exp_f32_e32 v91, v91
	v_exp_f32_e32 v156, v93
	v_exp_f32_e32 v157, v95
	v_exp_f32_e32 v158, v97
	v_exp_f32_e32 v128, v128
	v_exp_f32_e32 v159, v146
	v_exp_f32_e32 v160, v147
	v_exp_f32_e32 v161, v148
	v_exp_f32_e32 v162, v149
	v_add_u32_e32 v118, s38, v68
	v_lshl_add_u64 v[140:141], v[74:75], 0, s[4:5]
	v_lshl_add_u64 v[142:143], v[76:77], 0, s[4:5]
	v_lshl_add_u64 v[144:145], v[82:83], 0, s[4:5]
	v_mad_i64_i32 v[96:97], s[4:5], v118, s58, v[80:81]
	v_mfma_f32_32x32x2_f32 v[0:15], v94, v115, v[0:15]
	v_or_b32_e32 v93, 2, v118
	v_or_b32_e32 v115, 4, v118
	v_or_b32_e32 v148, 6, v118
	v_or_b32_e32 v150, 8, v118
	v_or_b32_e32 v152, 10, v118
	v_or_b32_e32 v153, 12, v118
	v_or_b32_e32 v118, 14, v118
	v_mad_i64_i32 v[146:147], s[4:5], v115, s58, v[80:81]
	v_mad_i64_i32 v[154:155], s[4:5], v118, s58, v[80:81]
	v_add_f32_e32 v85, 1.0, v85
	v_add_f32_e32 v87, 1.0, v87
	v_add_f32_e32 v89, 1.0, v89
	v_add_f32_e32 v91, 1.0, v91
	v_mfma_f32_32x32x2_f32 v[0:15], v92, v113, v[0:15]
	v_add_f32_e32 v113, 1.0, v156
	v_add_f32_e32 v115, 1.0, v157
	v_add_f32_e32 v118, 1.0, v158
	v_add_f32_e32 v128, 1.0, v128
	v_add_f32_e32 v156, 1.0, v159
	v_add_f32_e32 v157, 1.0, v160
	v_rcp_f32_e32 v85, v85
	v_rcp_f32_e32 v87, v87
	v_rcp_f32_e32 v89, v89
	v_rcp_f32_e32 v91, v91
	v_rcp_f32_e32 v113, v113
	v_rcp_f32_e32 v115, v115
	v_rcp_f32_e32 v118, v118
	v_rcp_f32_e32 v128, v128
	v_rcp_f32_e32 v156, v156
	v_mfma_f32_32x32x2_f32 v[0:15], v90, v111, v[0:15]
	v_add_f32_e32 v90, 1.0, v161
	v_add_f32_e32 v111, 1.0, v162
	v_rcp_f32_e32 v157, v157
	v_rcp_f32_e32 v90, v90
	v_rcp_f32_e32 v111, v111
	v_mul_f32_e32 v40, v40, v85
	v_mul_f32_e32 v41, v41, v87
	v_mul_f32_e32 v42, v42, v89
	v_mul_f32_e32 v43, v43, v91
	v_mul_f32_e32 v36, v36, v113
	v_mul_f32_e32 v37, v37, v115
	v_mul_f32_e32 v38, v38, v118
	v_mul_f32_e32 v39, v39, v128
	v_mul_f32_e32 v32, v32, v156
	v_mul_f32_e32 v33, v33, v157
	v_mfma_f32_32x32x2_f32 v[0:15], v88, v108, v[0:15]
	v_mul_f32_e32 v34, v34, v90
	v_mul_f32_e32 v35, v35, v111
	s_barrier
	v_mad_i64_i32 v[94:95], s[4:5], v93, s58, v[80:81]
	v_mad_i64_i32 v[148:149], s[4:5], v148, s58, v[80:81]
	v_mad_i64_i32 v[150:151], s[4:5], v150, s58, v[80:81]
	v_mad_i64_i32 v[92:93], s[4:5], v152, s58, v[80:81]
	v_mad_i64_i32 v[152:153], s[4:5], v153, s58, v[80:81]
	v_mfma_f32_32x32x2_f32 v[0:15], v86, v107, v[0:15]
	ds_write2_b32 v48, v40, v36 offset1:16
	ds_write2_b32 v48, v42, v38 offset0:130 offset1:146
	ds_write2_b32 v48, v32, v41 offset0:32 offset1:65
	ds_write2_b32 v48, v37, v33 offset0:81 offset1:97
	ds_write2_b32 v48, v34, v43 offset0:162 offset1:195
	ds_write2_b32 v48, v39, v35 offset0:211 offset1:227
	s_waitcnt lgkmcnt(0)
	s_barrier
	global_load_dwordx4 v[32:35], v[140:141], off
	global_load_dwordx4 v[36:39], v[142:143], off
	global_load_dwordx4 v[40:43], v[144:145], off
	global_load_dword v128, v[96:97], off
	global_load_dword v118, v[94:95], off
	global_load_dword v115, v[146:147], off
	global_load_dword v113, v[148:149], off
	global_load_dword v111, v[150:151], off
	global_load_dword v108, v[92:93], off
	global_load_dword v107, v[152:153], off
	v_mfma_f32_32x32x2_f32 v[0:15], v84, v116, v[0:15]
	global_load_dword v116, v[154:155], off
	ds_read2_b32 v[84:85], v109 offset1:32
	s_waitcnt lgkmcnt(0)
	v_mfma_f32_32x32x2_f32 v[0:15], v84, v135, v[0:15]
	v_mfma_f32_32x32x2_f32 v[16:31], v85, v135, v[16:31]
	ds_read2_b32 v[84:85], v109 offset0:130 offset1:162
	s_waitcnt lgkmcnt(0)
	v_mfma_f32_32x32x2_f32 v[0:15], v84, v134, v[0:15]
	v_mfma_f32_32x32x2_f32 v[16:31], v85, v134, v[16:31]
	ds_read2_b32 v[84:85], v139 offset0:4 offset1:36
	s_waitcnt lgkmcnt(0)
	v_mfma_f32_32x32x2_f32 v[0:15], v84, v133, v[0:15]
	v_mfma_f32_32x32x2_f32 v[16:31], v85, v133, v[16:31]
	ds_read2_b32 v[84:85], v139 offset0:134 offset1:166
	s_waitcnt lgkmcnt(0)
	v_mfma_f32_32x32x2_f32 v[0:15], v84, v132, v[0:15]
	v_mfma_f32_32x32x2_f32 v[16:31], v85, v132, v[16:31]
	ds_read2_b32 v[84:85], v138 offset0:8 offset1:40
	s_waitcnt lgkmcnt(0)
	v_mfma_f32_32x32x2_f32 v[0:15], v84, v131, v[0:15]
	v_mfma_f32_32x32x2_f32 v[16:31], v85, v131, v[16:31]
	ds_read2_b32 v[84:85], v138 offset0:138 offset1:170
	s_waitcnt lgkmcnt(0)
	v_mfma_f32_32x32x2_f32 v[0:15], v84, v130, v[0:15]
	v_mfma_f32_32x32x2_f32 v[16:31], v85, v130, v[16:31]
	ds_read2_b32 v[84:85], v137 offset0:12 offset1:44
	s_waitcnt lgkmcnt(0)
	v_mfma_f32_32x32x2_f32 v[0:15], v84, v129, v[0:15]
	v_mfma_f32_32x32x2_f32 v[16:31], v85, v129, v[16:31]
	ds_read2_b32 v[84:85], v137 offset0:142 offset1:174
	s_waitcnt lgkmcnt(0)
	v_mfma_f32_32x32x2_f32 v[0:15], v84, v136, v[0:15]
	v_mfma_f32_32x32x2_f32 v[16:31], v85, v136, v[16:31]
	s_mov_b64 s[38:39], 0
	s_cbranch_vccz .LBB0_93
	s_nop 15
	v_mul_lo_u32 v24, v79, s55
	v_lshlrev_b32_e32 v25, 9, v64
	v_or3_b32 v24, v25, v24, v72
	v_add_u32_e32 v25, 0x8000, v24
	ds_write2_b32 v25, v0, v1 offset0:192 offset1:224
	v_add_u32_e32 v0, 0x8400, v24
	ds_write2_b32 v0, v2, v3 offset1:32
	ds_write2_b32 v0, v4, v5 offset0:192 offset1:224
	v_add_u32_e32 v0, 0x8800, v24
	ds_write2_b32 v0, v6, v7 offset1:32
	ds_write2_b32 v0, v8, v9 offset0:192 offset1:224
	v_add_u32_e32 v0, 0x8c00, v24
	ds_write2_b32 v0, v10, v11 offset1:32
	ds_write2_b32 v0, v12, v13 offset0:192 offset1:224
	v_add_u32_e32 v0, 0x9000, v24
	ds_write2_b32 v0, v14, v15 offset1:32
	ds_write2_b32 v0, v16, v17 offset0:192 offset1:224
	v_add_u32_e32 v0, 0x9400, v24
	s_movk_i32 s4, 0x600
	ds_write2_b32 v0, v18, v19 offset1:32
	ds_write2_b32 v0, v20, v21 offset0:192 offset1:224
	v_add_u32_e32 v0, 0x9800, v24
	v_cmp_gt_i32_e32 vcc, s4, v70
	ds_write2_b32 v0, v22, v23 offset1:32
	s_waitcnt lgkmcnt(0)
	s_barrier
	s_and_saveexec_b64 s[4:5], vcc
	s_cbranch_execz .LBB0_22
	v_or_b32_e32 v0, v45, v78
	v_ashrrev_i32_e32 v1, 31, v0
	v_lshl_add_u64 v[2:3], v[0:1], 2, s[78:79]
	s_waitcnt vmcnt(0)
.LBB0_96:
	v_ashrrev_i32_e32 v4, 5, v70
	v_add_u32_e32 v6, 0x200, v70
	s_movk_i32 s42, 0x3ff
	v_lshl_or_b32 v10, v4, 7, v72
	v_cmp_lt_i32_e32 vcc, s42, v70
	v_mov_b32_e32 v70, v6
	v_add_u32_e32 v12, 0x8300, v10
	ds_read2st64_b32 v[6:7], v10 offset0:131 offset1:155
	ds_read2st64_b32 v[8:9], v10 offset0:179 offset1:203
	ds_read2st64_b32 v[10:11], v10 offset0:227 offset1:251
	ds_read2st64_b32 v[12:13], v12 offset0:144 offset1:168
	s_or_b64 s[38:39], vcc, s[38:39]
	s_waitcnt lgkmcnt(3)
	v_add_f32_e32 v6, 0, v6
	v_add_f32_e32 v6, v6, v7
	s_waitcnt lgkmcnt(2)
	v_add_f32_e32 v6, v6, v8
	v_add_f32_e32 v6, v6, v9
	s_waitcnt lgkmcnt(1)
	v_add_f32_e32 v6, v6, v10
	v_add_f32_e32 v6, v6, v11
	s_waitcnt lgkmcnt(0)
	v_add_f32_e32 v6, v6, v12
	v_add_f32_e32 v6, v6, v13
	v_mad_u64_u32 v[4:5], s[40:41], v4, s55, v[0:1]
	v_ashrrev_i32_e32 v5, 31, v4
	v_lshl_add_u64 v[4:5], v[4:5], 2, s[82:83]
	v_add_f32_e32 v1, v6, v200
	global_store_dword v[4:5], v1, off
	s_andn2_b64 exec, exec, s[38:39]
	s_cbranch_execnz .LBB0_96
	s_branch .LBB0_22
